# ring4+R4 + static s_setprio 1 for waves 4-7 during the attention KV loop
# speedup vs baseline: 1.0022x; 1.0022x over previous
.LBB0_397:
	s_and_b32 s45, s0, 15
	s_ashr_i32 s37, s36, 31
	s_mul_i32 s3, s36, 0x1800
	s_mul_hi_i32 s1, s36, 0x1800
	s_add_u32 s3, s78, s3
	v_readlane_b32 s2, v252, 50
	s_addc_u32 s1, s2, s1
	s_lshl_b32 s5, s45, 7
	s_add_u32 s30, s3, s5
	s_addc_u32 s31, s1, 0
	v_readlane_b32 s2, v250, 19
	v_readlane_b32 s3, v250, 20
	s_add_u32 s28, s2, s5
	v_mov_b32_e32 v6, v168
	s_addc_u32 s29, s3, 0
	s_lshl_b32 s0, s0, 7
	s_and_b32 s0, s0, 0x700
	v_ashrrev_i32_e32 v0, 6, v6
	v_and_b32_e32 v62, 63, v6
	v_and_b32_e32 v1, 0x3fffffc0, v6
	v_and_b32_e32 v200, 31, v6
	v_lshl_add_u32 v175, v1, 2, v192
	v_lshl_add_u32 v1, v0, 12, v192
	v_lshlrev_b32_e32 v7, 4, v62
	v_lshlrev_b32_e32 v174, 5, v0
	s_add_u32 s39, s73, s0
	v_bfe_u32 v201, v6, 5, 1
	v_add_u32_e32 v204, v1, v7
	v_or_b32_e32 v2, v174, v200
	v_mov_b64_e32 v[0:1], s[30:31]
	s_movk_i32 s0, 0x1800
	v_mad_i64_i32 v[0:1], s[0:1], v2, s0, v[0:1]
	v_lshlrev_b32_e32 v176, 4, v201
	v_mov_b32_e32 v177, v171
	v_lshl_add_u64 v[4:5], v[0:1], 0, v[176:177]
	global_load_dwordx4 v[0:3], v[4:5], off
	v_lshlrev_b32_e32 v12, 3, v6
	s_movk_i32 s1, 0xe0
	s_mov_b32 s0, 0x7ffffc
	s_addc_u32 s42, s63, 0
	s_cmp_lg_u32 0x100, -1
	s_mul_i32 s44, s38, 0x1800
	s_mul_hi_i32 s43, s38, 0x1800
	v_and_b32_e32 v8, 0x70, v6
	v_lshlrev_b32_e32 v72, 7, v200
	v_and_b32_e32 v73, 0x70, v12
	v_or_b32_e32 v64, 32, v176
	v_bitop3_b32 v64, v64, v72, v73 bitop3:0xde
	v_add_u32_e32 v209, 0x100, v64
	s_mov_b32 s5, s4
	s_mov_b32 s10, s4
	s_mov_b32 s11, s4
	s_mov_b32 s12, s4
	s_mov_b32 s13, s4
	s_mov_b32 s14, s4
	s_mov_b32 s15, s4
	s_mov_b32 s16, s4
	s_mov_b32 s17, s4
	s_mov_b32 s18, s4
	s_mov_b32 s19, s4
	v_mov_b32_e32 v61, v171
	v_cmp_gt_u32_e64 s[40:41], 32, v62
	s_mov_b32 s50, 4
	s_movk_i32 s51, 0xc0
	v_lshl_add_u32 v177, v200, 2, v175
	v_mov_b32_e32 v178, 0
	s_waitcnt vmcnt(0)
	ds_write_b128 v204, v[0:3] offset:51200
	global_load_dwordx4 v[0:3], v[4:5], off offset:32
	s_waitcnt vmcnt(0)
	ds_write_b128 v204, v[0:3] offset:52224
	global_load_dwordx4 v[0:3], v[4:5], off offset:64
	s_waitcnt vmcnt(0)
	ds_write_b128 v204, v[0:3] offset:53248
	global_load_dwordx4 v[0:3], v[4:5], off offset:96
	v_and_b32_e32 v5, 24, v12
	s_waitcnt vmcnt(0)
	ds_write_b128 v204, v[0:3] offset:54272
	v_ashrrev_i32_e32 v0, 4, v6
	v_lshlrev_b32_e32 v4, 5, v0
	v_lshrrev_b32_e32 v2, 5, v6
	v_bfe_u32 v3, v12, 5, 2
	v_and_or_b32 v4, v4, s1, v5
	v_and_or_b32 v2, v2, s0, v3
	v_lshlrev_b32_e32 v4, 1, v4
	v_lshl_or_b32 v13, v2, 9, v4
	v_add_u32_e32 v2, 32, v0
	v_lshrrev_b32_e32 v2, 1, v2
	v_and_or_b32 v2, v2, s0, v3
	s_movk_i32 s0, 0xc00
	v_and_b32_e32 v1, 0x78, v12
	v_mul_lo_u32 v0, v0, s0
	v_lshl_or_b32 v14, v2, 9, v4
	v_ashrrev_i32_e32 v2, 3, v6
	v_or_b32_e32 v0, v0, v1
	v_and_b32_e32 v3, 56, v12
	v_lshlrev_b32_e32 v170, 1, v0
	v_mul_lo_u32 v0, v2, s0
	v_or_b32_e32 v0, v0, v3
	s_cselect_b32 s0, 0x100, 0
	s_add_u32 s6, s39, s44
	v_lshlrev_b32_e32 v4, 7, v2
	v_lshlrev_b32_e32 v5, 1, v3
	v_lshlrev_b32_e32 v60, 1, v0
	v_lshlrev_b32_e32 v0, 3, v62
	v_and_b32_e32 v1, 0xc0, v7
	v_lshlrev_b32_e32 v2, 1, v6
	s_addc_u32 s7, s42, s43
	v_bitop3_b32 v15, v5, v4, v8 bitop3:0xde
	v_and_or_b32 v1, v0, 24, v1
	v_and_b32_e32 v2, 32, v2
	v_and_b32_e32 v0, 0x100, v0
	v_lshl_add_u64 v[4:5], s[6:7], 0, v[170:171]
	v_or3_b32 v63, v1, v2, v0
	s_add_u32 s8, s28, s44
	global_load_dwordx4 v[0:3], v170, s[6:7]
	v_add_co_u32_e32 v4, vcc, s33, v4
	s_addc_u32 s9, s29, s43
	s_nop 0
	v_addc_co_u32_e32 v5, vcc, 0, v5, vcc
	global_load_dwordx4 v[4:7], v[4:5], off
	v_add_u32_e32 v205, 0x100, v13
	global_load_dwordx4 v[8:11], v60, s[8:9]
	s_waitcnt vmcnt(0)
	v_add_u32_e32 v206, 0x100, v14
	v_add_u32_e32 v207, 0x100, v15
	s_mov_b32 s6, s4
	s_mov_b32 s7, s4
	s_mov_b32 s8, s4
	s_mov_b32 s9, s4
	s_add_i32 s1, s38, 64
	v_add_u32_e32 v203, s0, v63
	v_lshl_add_u64 v[180:181], s[28:29], 0, v[60:61]
	s_waitcnt vmcnt(2)
	ds_write_b128 v205, v[0:3]
	v_bitop3_b32 v0, v176, v72, v73 bitop3:0xde
	v_add_u32_e32 v208, 0x100, v0
	s_waitcnt vmcnt(1)
	ds_write_b128 v206, v[4:7]
	s_waitcnt vmcnt(0)
	ds_write_b128 v207, v[8:11] offset:32768
	s_waitcnt lgkmcnt(0)
	s_barrier
	ds_read_b128 v[56:59], v204 offset:52224
	ds_read_b128 v[52:55], v204 offset:53248
	ds_read_b128 v[48:51], v204 offset:54272
	ds_read_b128 v[16:19], v208 offset:36864
	ds_read_b128 v[20:23], v208 offset:32768
	ds_read_b128 v[24:27], v204 offset:51200
	s_waitcnt lgkmcnt(0)
	v_mfma_f32_32x32x16_bf16 v[32:47], v[20:23], v[24:27], 0
	ds_read_b128 v[64:67], v209 offset:36864
	ds_read_b128 v[68:71], v209 offset:32768
	v_mov_b64_e32 v[0:1], s[4:5]
	v_mov_b64_e32 v[2:3], s[6:7]
	v_mov_b64_e32 v[4:5], s[8:9]
	v_mov_b64_e32 v[6:7], s[10:11]
	v_mov_b64_e32 v[8:9], s[12:13]
	v_mov_b64_e32 v[10:11], s[14:15]
	v_mfma_f32_32x32x16_bf16 v[16:31], v[16:19], v[24:27], 0
	v_mov_b64_e32 v[12:13], s[16:17]
	v_mov_b64_e32 v[14:15], s[18:19]
	s_add_i32 s12, s44, 0x60000
	s_mul_hi_i32 s5, s1, 0x1800
	s_add_u32 s6, s39, s12
	s_addc_u32 s7, s42, s5
	s_add_u32 s8, s28, s12
	s_waitcnt lgkmcnt(0)
	v_mfma_f32_32x32x16_bf16 v[32:47], v[68:71], v[56:59], v[32:47]
	s_addc_u32 s9, s29, s5
	s_add_i32 s1, s38, 0x80
	s_add_i32 s47, s44, 0xc0000
	s_mul_hi_i32 s46, s1, 0x1800
	v_mfma_f32_32x32x16_bf16 v[16:31], v[64:67], v[56:59], v[16:31]
	v_or_b32_e32 v56, 64, v176
	v_bitop3_b32 v56, v56, v72, v73 bitop3:0xde
	v_add_u32_e32 v210, 0x100, v56
	ds_read_b128 v[56:59], v210 offset:36864
	ds_read_b128 v[64:67], v210 offset:32768
	s_waitcnt lgkmcnt(0)
	v_mfma_f32_32x32x16_bf16 v[32:47], v[64:67], v[52:55], v[32:47]
	v_mfma_f32_32x32x16_bf16 v[16:31], v[56:59], v[52:55], v[16:31]
	v_or_b32_e32 v52, 0x60, v176
	v_bitop3_b32 v52, v52, v72, v73 bitop3:0xde
	v_add_u32_e32 v211, 0x100, v52
	ds_read_b128 v[52:55], v211 offset:36864
	ds_read_b128 v[56:59], v211 offset:32768
	s_waitcnt lgkmcnt(0)
	v_mfma_f32_32x32x16_bf16 v[32:47], v[56:59], v[48:51], v[32:47]
	v_mfma_f32_32x32x16_bf16 v[16:31], v[52:55], v[48:51], v[16:31]
	s_nop 10
	v_max_f32_e32 v48, v33, v33
	v_max_f32_e32 v49, v32, v32
	v_max_f32_e32 v48, v49, v48
	v_max3_f32 v48, v48, v34, v35
	v_max3_f32 v48, v48, v36, v37
	v_max3_f32 v48, v48, v38, v39
	v_max3_f32 v48, v48, v40, v41
	v_max3_f32 v48, v48, v42, v43
	v_max3_f32 v48, v48, v44, v45
	v_max3_f32 v48, v48, v46, v47
	v_max3_f32 v48, v48, v16, v17
	v_max3_f32 v48, v48, v18, v19
	v_max3_f32 v48, v48, v20, v21
	v_max3_f32 v48, v48, v22, v23
	v_max3_f32 v48, v48, v24, v25
	v_max3_f32 v48, v48, v26, v27
	v_max3_f32 v48, v48, v28, v29
	v_max3_f32 v48, v48, v30, v31
	v_mov_b32_e32 v49, v48
	s_nop 1
	v_permlane32_swap_b32_e32 v48, v49
	v_max_f32_e32 v49, v49, v49
	v_max_f32_e32 v48, v48, v48
	v_max_f32_e32 v48, v48, v49
	v_sub_f32_e32 v36, v36, v48
	v_sub_f32_e32 v37, v37, v48
	v_exp_f32_e32 v53, v36
	v_exp_f32_e32 v54, v37
	v_lshl_add_u64 v[36:37], s[6:7], 0, v[170:171]
	v_add_co_u32_e32 v36, vcc, s33, v36
	v_sub_f32_e32 v32, v32, v48
	v_sub_f32_e32 v33, v33, v48
	v_sub_f32_e32 v34, v34, v48
	v_sub_f32_e32 v35, v35, v48
	v_sub_f32_e32 v38, v38, v48
	v_sub_f32_e32 v39, v39, v48
	v_sub_f32_e32 v40, v40, v48
	v_sub_f32_e32 v41, v41, v48
	v_sub_f32_e32 v42, v42, v48
	v_sub_f32_e32 v43, v43, v48
	v_sub_f32_e32 v44, v44, v48
	v_sub_f32_e32 v45, v45, v48
	v_sub_f32_e32 v46, v46, v48
	v_sub_f32_e32 v47, v47, v48
	v_addc_co_u32_e32 v37, vcc, 0, v37, vcc
	v_exp_f32_e32 v49, v32
	v_exp_f32_e32 v50, v33
	v_exp_f32_e32 v51, v34
	v_exp_f32_e32 v52, v35
	v_exp_f32_e32 v55, v38
	v_exp_f32_e32 v56, v39
	v_exp_f32_e32 v57, v40
	v_exp_f32_e32 v58, v41
	v_exp_f32_e32 v59, v42
	v_exp_f32_e32 v64, v43
	v_exp_f32_e32 v65, v44
	v_exp_f32_e32 v66, v45
	v_exp_f32_e32 v46, v46
	v_exp_f32_e32 v47, v47
	v_cvt_pk_bf16_f32 v144, v49, v50
	v_cvt_pk_bf16_f32 v145, v51, v52
	v_cvt_pk_bf16_f32 v146, v53, v54
	v_cvt_pk_bf16_f32 v147, v55, v56
	v_cvt_pk_bf16_f32 v140, v57, v58
	v_cvt_pk_bf16_f32 v141, v59, v64
	v_cvt_pk_bf16_f32 v142, v65, v66
	v_cvt_pk_bf16_f32 v143, v46, v47
	global_load_dwordx4 v[32:35], v170, s[6:7]
	s_nop 0
	global_load_dwordx4 v[36:39], v[36:37], off
	s_nop 0
	global_load_dwordx4 v[40:43], v60, s[8:9]
	s_add_u32 s6, s28, s47
	s_addc_u32 s7, s29, s46
	global_load_dwordx4 v[128:131], v60, s[6:7]
	s_add_u32 s6, s39, s47
	s_addc_u32 s7, s42, s46
	v_lshl_add_u64 v[44:45], s[6:7], 0, v[170:171]
	v_add_co_u32_e32 v44, vcc, s33, v44
	v_add_f32_e32 v212, 0, v48
	s_nop 0
	v_addc_co_u32_e32 v45, vcc, 0, v45, vcc
	global_load_dwordx4 v[136:139], v[44:45], off
	global_load_dwordx4 v[132:135], v170, s[6:7]
	s_waitcnt vmcnt(3)
	s_waitcnt vmcnt(5)
	ds_write_b128 v205, v[32:35] offset:16384
	s_waitcnt vmcnt(4)
	ds_write_b128 v206, v[36:39] offset:16384
	s_waitcnt vmcnt(3)
	ds_write_b128 v207, v[40:43] offset:40960
	v_add_f32_e32 v32, 0, v49
	v_add_f32_e32 v32, v50, v32
	v_add_f32_e32 v32, v51, v32
	v_add_f32_e32 v32, v52, v32
	v_add_f32_e32 v32, v53, v32
	v_add_f32_e32 v32, v54, v32
	v_add_f32_e32 v32, v55, v32
	v_add_f32_e32 v32, v56, v32
	v_add_f32_e32 v32, v57, v32
	v_add_f32_e32 v32, v58, v32
	v_add_f32_e32 v32, v59, v32
	v_add_f32_e32 v32, v64, v32
	v_add_f32_e32 v32, v65, v32
	v_add_f32_e32 v32, v66, v32
	v_add_f32_e32 v32, v46, v32
	s_addk_i32 s0, 0x4000
	v_xor_b32_e32 v96, 0x80000000, v212
	v_add_f32_e32 v164, v47, v32
	v_sub_f32_e32 v95, v31, v48
	v_sub_f32_e32 v94, v30, v48
	v_sub_f32_e32 v93, v29, v48
	v_sub_f32_e32 v92, v28, v48
	v_sub_f32_e32 v91, v27, v48
	v_sub_f32_e32 v90, v26, v48
	v_sub_f32_e32 v89, v25, v48
	v_sub_f32_e32 v88, v24, v48
	v_sub_f32_e32 v87, v23, v48
	v_sub_f32_e32 v86, v22, v48
	v_sub_f32_e32 v85, v21, v48
	v_sub_f32_e32 v84, v20, v48
	v_sub_f32_e32 v83, v19, v48
	v_sub_f32_e32 v82, v18, v48
	v_sub_f32_e32 v81, v17, v48
	v_sub_f32_e32 v80, v16, v48
	v_add_u32_e32 v202, s0, v63
	v_mov_b64_e32 v[62:63], v[14:15]
	v_mov_b64_e32 v[46:47], v[14:15]
	v_mov_b64_e32 v[30:31], v[14:15]
	s_mov_b64 s[8:9], 0
	v_mov_b64_e32 v[60:61], v[12:13]
	v_mov_b64_e32 v[58:59], v[10:11]
	v_mov_b64_e32 v[56:57], v[8:9]
	v_mov_b64_e32 v[54:55], v[6:7]
	v_mov_b64_e32 v[52:53], v[4:5]
	v_mov_b64_e32 v[50:51], v[2:3]
	v_mov_b64_e32 v[48:49], v[0:1]
	v_mov_b64_e32 v[44:45], v[12:13]
	v_mov_b64_e32 v[42:43], v[10:11]
	v_mov_b64_e32 v[40:41], v[8:9]
	v_mov_b64_e32 v[38:39], v[6:7]
	v_mov_b64_e32 v[36:37], v[4:5]
	v_mov_b64_e32 v[34:35], v[2:3]
	v_mov_b64_e32 v[32:33], v[0:1]
	v_mov_b64_e32 v[28:29], v[12:13]
	v_mov_b64_e32 v[26:27], v[10:11]
	v_mov_b64_e32 v[24:25], v[8:9]
	v_mov_b64_e32 v[22:23], v[6:7]
	v_mov_b64_e32 v[20:21], v[4:5]
	v_mov_b64_e32 v[18:19], v[2:3]
	v_mov_b64_e32 v[16:17], v[0:1]
	v_mov_b32_e32 v97, v96
	v_mov_b32_e32 v98, v96
	v_mov_b32_e32 v99, v96
	v_mov_b32_e32 v100, v96
	v_mov_b32_e32 v101, v96
	v_mov_b32_e32 v102, v96
	v_mov_b32_e32 v103, v96
	v_mov_b32_e32 v104, v96
	v_mov_b32_e32 v105, v96
	v_mov_b32_e32 v106, v96
	v_mov_b32_e32 v107, v96
	v_mov_b32_e32 v108, v96
	v_mov_b32_e32 v109, v96
	v_mov_b32_e32 v110, v96
	v_mov_b32_e32 v111, v96
	s_waitcnt lgkmcnt(0)
	s_barrier
	s_mov_b32 s100, 0x14800
	s_mov_b32 s101, 0x18010
	v_add_u32_e32 v205, s100, v205
	v_add_u32_e32 v206, s100, v206
	v_add_u32_e32 v207, s101, v207
	v_readfirstlane_b32 s0, v168
	s_nop 3
	s_lshr_b32 s0, s0, 8
	s_cmp_lg_u32 s0, 0
	s_cbranch_scc0 .Lprio_skip
	s_setprio 1
.Lprio_skip:
.LBB0_398:
	ds_read_b128 v[64:67], v208 offset:40960
	ds_read_b128 v[68:71], v204 offset:51200
	ds_read_b128 v[72:75], v204 offset:52224
	ds_read_b128 v[76:79], v208 offset:45056
	v_exp_f32_e32 v148, v80
	v_exp_f32_e32 v149, v81
	s_waitcnt lgkmcnt(2)
	v_mfma_f32_32x32x16_bf16 v[112:127], v[64:67], v[68:71], v[96:111]
	ds_read_b128 v[64:67], v209 offset:40960
	ds_read_b128 v[182:185], v209 offset:45056
	ds_read_b128 v[150:153], v210 offset:40960
	v_exp_f32_e32 v154, v84
	v_exp_f32_e32 v155, v85
	v_exp_f32_e32 v158, v86
	v_exp_f32_e32 v159, v87
	v_exp_f32_e32 v156, v90
	v_exp_f32_e32 v157, v91
	s_waitcnt lgkmcnt(2)
	v_mfma_f32_32x32x16_bf16 v[112:127], v[64:67], v[72:75], v[112:127]
	ds_read_b128 v[64:67], v210 offset:45056
	ds_read_b128 v[186:189], v204 offset:53248
	ds_read_b128 v[214:217], v204 offset:54272
	ds_read_b128 v[218:221], v211 offset:45056
	ds_read_b128 v[160:163], v211 offset:40960
	v_exp_f32_e32 v166, v94
	v_exp_f32_e32 v167, v95
	s_waitcnt lgkmcnt(3)
	v_mfma_f32_32x32x16_bf16 v[112:127], v[150:153], v[186:189], v[112:127]
	v_exp_f32_e32 v152, v82
	v_exp_f32_e32 v153, v83
	v_exp_f32_e32 v150, v88
	v_exp_f32_e32 v151, v89
	s_waitcnt lgkmcnt(0)
	v_mfma_f32_32x32x16_bf16 v[112:127], v[160:163], v[214:217], v[112:127]
	v_exp_f32_e32 v162, v92
	v_exp_f32_e32 v163, v93
	v_mfma_f32_32x32x16_bf16 v[80:95], v[76:79], v[68:71], v[96:111]
	v_add_f32_e32 v68, v164, v148
	v_add_f32_e32 v68, v149, v68
	v_add_f32_e32 v68, v152, v68
	v_add_f32_e32 v68, v153, v68
	v_add_f32_e32 v68, v154, v68
	v_add_f32_e32 v68, v155, v68
	v_add_f32_e32 v68, v158, v68
	v_mfma_f32_32x32x16_bf16 v[80:95], v[182:185], v[72:75], v[80:95]
	v_add_f32_e32 v68, v159, v68
	v_add_f32_e32 v68, v150, v68
	v_add_f32_e32 v68, v151, v68
	v_add_f32_e32 v68, v156, v68
	v_add_f32_e32 v68, v157, v68
	v_add_f32_e32 v68, v162, v68
	v_add_f32_e32 v68, v163, v68
	v_mfma_f32_32x32x16_bf16 v[80:95], v[64:67], v[186:189], v[80:95]
	v_add_f32_e32 v64, v166, v68
	v_add_f32_e32 v64, v167, v64
	v_mov_b32_e32 v65, v64
	s_nop 1
	v_permlane32_swap_b32_e32 v64, v65
	v_add_f32_e32 v164, v64, v65
	v_cmp_ge_f32_e32 vcc, s99, v164
	v_mfma_f32_32x32x16_bf16 v[80:95], v[218:221], v[214:217], v[80:95]
	s_cmp_eq_u64 vcc, exec
	s_cbranch_scc0 .LBB0_405

.LBB0_411:
	s_setprio 0
	v_mov_b64_e32 v[64:65], v[96:97]
	v_mov_b64_e32 v[66:67], v[98:99]
	v_mov_b64_e32 v[68:69], v[100:101]
	v_mov_b64_e32 v[70:71], v[102:103]
	v_mov_b64_e32 v[72:73], v[104:105]
	v_mov_b64_e32 v[74:75], v[106:107]
	v_mov_b64_e32 v[76:77], v[108:109]
	v_mov_b64_e32 v[78:79], v[110:111]
	ds_read_b128 v[120:123], v204 offset:52224
	ds_read_b128 v[124:127], v204 offset:53248
	ds_read_b128 v[128:131], v204 offset:54272
	ds_read_b128 v[132:135], v208 offset:45056
	ds_read_b128 v[112:115], v208 offset:40960
	ds_read_b128 v[136:139], v204 offset:51200
	v_exp_f32_e32 v118, v82
	v_exp_f32_e32 v119, v83
	v_exp_f32_e32 v116, v84
	v_exp_f32_e32 v117, v85
	s_waitcnt lgkmcnt(0)
	v_mfma_f32_32x32x16_bf16 v[96:111], v[112:115], v[136:139], v[64:79]
	ds_read_b128 v[148:151], v209 offset:45056
	ds_read_b128 v[112:115], v209 offset:40960
	v_exp_f32_e32 v84, v92
	v_exp_f32_e32 v85, v93
	v_exp_f32_e32 v82, v94
	v_exp_f32_e32 v83, v95
	s_waitcnt lgkmcnt(0)
	v_mfma_f32_32x32x16_bf16 v[96:111], v[112:115], v[120:123], v[96:111]
	ds_read_b128 v[152:155], v210 offset:45056
	ds_read_b128 v[112:115], v210 offset:40960
	s_waitcnt lgkmcnt(0)
	v_mfma_f32_32x32x16_bf16 v[96:111], v[112:115], v[124:127], v[96:111]
	ds_read_b128 v[156:159], v211 offset:45056
	ds_read_b128 v[112:115], v211 offset:40960
	v_mfma_f32_32x32x16_bf16 v[64:79], v[132:135], v[136:139], v[64:79]
	s_waitcnt lgkmcnt(0)
	v_mfma_f32_32x32x16_bf16 v[96:111], v[112:115], v[128:131], v[96:111]
	v_exp_f32_e32 v112, v80
	v_exp_f32_e32 v113, v81
	v_exp_f32_e32 v80, v88
	v_exp_f32_e32 v114, v86
	v_add_f32_e32 v88, v112, v164
	v_add_f32_e32 v88, v113, v88
	v_add_f32_e32 v88, v118, v88
	v_mfma_f32_32x32x16_bf16 v[64:79], v[148:151], v[120:123], v[64:79]
	v_exp_f32_e32 v115, v87
	v_add_f32_e32 v88, v119, v88
	v_add_f32_e32 v88, v116, v88
	v_exp_f32_e32 v81, v89
	v_add_f32_e32 v88, v117, v88
	v_exp_f32_e32 v86, v90
	v_add_f32_e32 v88, v114, v88
	v_mfma_f32_32x32x16_bf16 v[64:79], v[152:155], v[124:127], v[64:79]
	v_exp_f32_e32 v87, v91
	v_add_f32_e32 v88, v115, v88
	v_add_f32_e32 v88, v80, v88
	v_add_f32_e32 v88, v81, v88
	v_add_f32_e32 v88, v86, v88
	v_add_f32_e32 v88, v87, v88
	v_add_f32_e32 v88, v84, v88
	v_add_f32_e32 v88, v85, v88
	v_mfma_f32_32x32x16_bf16 v[64:79], v[156:159], v[128:131], v[64:79]
	v_add_f32_e32 v88, v82, v88
	v_add_f32_e32 v88, v83, v88
	v_mov_b32_e32 v89, v88
	s_nop 1
	v_permlane32_swap_b32_e32 v88, v89
	v_add_f32_e32 v88, v88, v89
	v_cmp_ge_f32_e32 vcc, s99, v88
	s_cmp_lg_u64 vcc, exec
	s_cbranch_scc1 .LBB0_450
